# stack of instruction-count trims: SGPR-base addressing in four GEMM K-loops and both attention prefetch streams, never-blocking lgkmcnt waits dropped, staging address add folded
# baseline (speedup 1.0000x reference)
.LBB0_330:
	s_cmpk_gt_i32 s2, 0x7ff
	s_cbranch_scc1 .LBB0_376
	v_mbcnt_lo_u32_b32 v0, -1, 0
	v_mbcnt_hi_u32_b32 v0, -1, v0
	v_lshlrev_b32_e32 v1, 2, v0
	v_and_b32_e32 v2, 31, v0
	v_lshlrev_b32_e32 v2, 2, v2
	v_add_u32_e32 v2, 0x100, v2
	v_readlane_b32 s0, v242, 15
	v_readlane_b32 s1, v242, 16
	v_readlane_b32 s40, v242, 17
	v_readlane_b32 s41, v242, 18
	v_readlane_b32 s46, v242, 19
	v_readlane_b32 s47, v242, 20
	v_readlane_b32 s96, v242, 21
	v_readlane_b32 s97, v242, 22
	s_nop 4
	global_load_dword v3, v1, s[0:1]
	global_load_dword v4, v2, s[0:1]
	global_load_dword v5, v1, s[40:41]
	global_load_dword v6, v2, s[40:41]
	global_load_dword v7, v1, s[46:47]
	global_load_dword v8, v1, s[96:97]
	s_waitcnt vmcnt(0)
	v_max3_f32 v3, |v3|, |v4|, |v5|
	v_max3_f32 v6, |v6|, |v7|, |v8|
	v_max_f32_e32 v3, v3, v6
	v_xor_b32_e32 v4, 4, v1
	ds_bpermute_b32 v5, v4, v3
	s_waitcnt lgkmcnt(0)
	v_max_f32_e32 v3, v3, v5
	v_xor_b32_e32 v4, 8, v1
	ds_bpermute_b32 v5, v4, v3
	s_waitcnt lgkmcnt(0)
	v_max_f32_e32 v3, v3, v5
	v_xor_b32_e32 v4, 16, v1
	ds_bpermute_b32 v5, v4, v3
	s_waitcnt lgkmcnt(0)
	v_max_f32_e32 v3, v3, v5
	v_xor_b32_e32 v4, 32, v1
	ds_bpermute_b32 v5, v4, v3
	s_waitcnt lgkmcnt(0)
	v_max_f32_e32 v3, v3, v5
	v_xor_b32_e32 v4, 64, v1
	ds_bpermute_b32 v5, v4, v3
	s_waitcnt lgkmcnt(0)
	v_max_f32_e32 v3, v3, v5
	v_xor_b32_e32 v4, 128, v1
	ds_bpermute_b32 v5, v4, v3
	s_waitcnt lgkmcnt(0)
	v_max_f32_e32 v3, v3, v5
	v_mul_f32_e32 v3, v3, v3
	v_mul_f32_e32 v4, 0x413c5bb7, v3
	v_mul_f32_e32 v5, 0x4166b0d9, v3
	s_nop 0
	v_readfirstlane_b32 s99, v4
	v_readfirstlane_b32 s100, v5
	s_lshl_b32 s0, s2, 5
	s_and_b32 s0, s0, 0x400
	s_cmpk_eq_i32 s30, 0x100
	s_cselect_b32 s46, s0, 0x100
	s_add_u32 s47, s26, 0xc000000
	s_addc_u32 s70, s27, 0
	s_add_u32 s96, s26, 0x17000000
	s_addc_u32 s97, s27, 0
	s_add_u32 s40, s26, 0x11000000
	s_addc_u32 s41, s27, 0
	s_add_u32 s92, s26, 0x1a000000
	s_addc_u32 s93, s27, 0
	s_add_u32 s66, s26, 0x13000000
	s_addc_u32 s67, s27, 0
	v_writelane_b32 v242, s4, 39
	s_add_u32 s69, s26, 0x1a800000
	s_addc_u32 s10, s27, 0
	v_writelane_b32 v242, s5, 40
	v_lshrrev_b32_e32 v3, 3, v168
	v_lshlrev_b32_e32 v0, 4, v168
	v_writelane_b32 v242, s82, 37
	s_add_u32 s11, s26, 0x90000
	v_and_b32_e32 v1, 0x70, v0
	v_and_b32_e32 v5, 0x60, v0
	v_lshlrev_b32_e32 v4, 3, v168
	v_mul_u32_u24_e32 v8, 0x90, v3
	v_writelane_b32 v242, s83, 38
	s_addc_u32 s0, s27, 0
	v_and_b32_e32 v6, 8, v4
	v_add3_u32 v177, v8, v1, 0
	v_add_u32_e32 v1, 0, v5
	v_add_u32_e32 v5, 0x200, v168
	v_writelane_b32 v242, s0, 36
	v_add3_u32 v198, v1, v6, v8
	v_mul_u32_u24_e32 v6, 0x1556, v5
	v_and_b32_e32 v170, 31, v168
	v_lshrrev_b32_e32 v171, 5, v169
	v_readlane_b32 s0, v242, 33
	v_mul_u32_u24_e32 v1, 0x1556, v168
	v_lshrrev_b32_e32 v6, 16, v6
	s_lshl_b32 s14, s0, 5
	v_lshlrev_b32_e32 v7, 4, v171
	v_lshrrev_b32_e32 v1, 16, v1
	v_add_lshl_u32 v206, v5, v6, 4
	v_mul_u32_u24_e32 v5, 0xd0, v170
	v_mov_b32_e32 v173, 0
	s_add_u32 s0, s26, 0x70000
	v_add_lshl_u32 v207, v168, v1, 4
	v_add3_u32 v208, 0, v5, v7
	v_lshlrev_b32_e32 v1, 6, v170
	v_and_b32_e32 v5, 7, v168
	s_movk_i32 s1, 0x100
	v_or_b32_e32 v172, s14, v170
	v_writelane_b32 v242, s0, 33
	s_addc_u32 s0, s27, 0
	v_sub_u32_e32 v209, v208, v1
	v_mov_b32_e32 v1, v173
	v_lshlrev_b32_e32 v5, 4, v5
	v_mul_u32_u24_e32 v9, 0x90, v170
	v_lshlrev_b64 v[174:175], 11, v[172:173]
	v_writelane_b32 v242, s0, 34
	v_cmp_gt_u32_e64 s[4:5], s1, v168
	v_lshl_add_u64 v[0:1], s[26:27], 0, v[0:1]
	s_mov_b64 s[0:1], 0x1a006000
	v_lshl_or_b32 v172, v3, 16, v5
	v_add3_u32 v199, v7, v9, 0
	v_lshl_add_u64 v[178:179], v[0:1], 0, s[0:1]
	v_lshl_add_u64 v[6:7], s[26:27], 0, v[172:173]
	s_mov_b64 s[0:1], 0x13000180
	v_lshl_add_u64 v[180:181], v[6:7], 0, s[0:1]
	s_mov_b64 s[0:1], 0x1700b000
	v_cmp_gt_u32_e64 s[6:7], 32, v169
	v_exp_f32_e32 v169, 0xbfd49a78
	v_exp_f32_e32 v200, 0xc0549a78
	v_exp_f32_e32 v201, 0xc09f73da
	v_exp_f32_e32 v202, 0xc0d49a78
	v_exp_f32_e32 v203, 0xc104e08b
	v_exp_f32_e32 v204, 0xc11f73da
	v_exp_f32_e32 v205, 0xc13a0729
	v_lshl_add_u64 v[182:183], v[0:1], 0, s[0:1]
	v_mbcnt_lo_u32_b32 v0, -1, 0
	v_mbcnt_hi_u32_b32 v212, -1, v0
	v_lshlrev_b32_e32 v2, 15, v3
	s_mov_b32 s17, 0
	v_and_b32_e32 v4, 56, v4
	s_mov_b64 s[0:1], 0x11000180
	v_and_b32_e32 v0, 64, v212
	s_mov_b32 s15, s17
	v_lshlrev_b32_e32 v176, 3, v171
	v_lshl_add_u64 v[184:185], v[6:7], 0, s[0:1]
	v_mov_b32_e32 v210, 0x358637bd
	s_mov_b32 s64, 0xf800000
	v_mov_b32_e32 v211, 0x260
	s_mov_b32 s65, 0x3e38aa3b
	s_mov_b32 s68, 0x41000000
	s_mov_b64 s[20:21], 0x2000
	s_mov_b64 s[22:23], 0x80
	s_mov_b32 s71, 0x3e16c740
	s_mov_b64 s[36:37], 0x3000
	v_xor_b32_e32 v213, 32, v212
	v_add_u32_e32 v214, 64, v0
	v_lshlrev_b32_e32 v172, 1, v2
	v_lshlrev_b32_e32 v186, 1, v4
	v_lshlrev_b32_e32 v188, 4, v168
	v_add_u32_e32 v215, 0x4800, v198
	v_add_u32_e32 v244, 0x9800, v198
	v_add_u32_e32 v216, 0x6800, v198
	v_mov_b32_e32 v217, 0x60000
	s_branch .LBB0_334

.Lstg_y_2:
	ds_read_b128 v[160:163], v199 offset:9216
	ds_read_b128 v[156:159], v199 offset:9248
	ds_read_b128 v[164:167], v199 offset:13824
	ds_read_b128 v[152:155], v199 offset:13856
	ds_read_b128 v[144:147], v199 offset:9280
	ds_read_b128 v[140:143], v199 offset:9312
	ds_read_b128 v[148:151], v199 offset:13888
	ds_read_b128 v[136:139], v199 offset:13920
	s_waitcnt lgkmcnt(14)
	v_mfma_f32_32x32x16_bf16 v[16:31], v[96:99], v[0:3], 0
	s_waitcnt vmcnt(1)
	ds_write_b128 v177, v[52:55]
	s_waitcnt vmcnt(0)
	ds_write2_b64 v215, v[48:49], v[50:51] offset1:2
	s_waitcnt lgkmcnt(14)
	v_mfma_f32_32x32x16_bf16 v[0:15], v[100:103], v[0:3], 0
	v_mfma_f32_32x32x16_bf16 v[16:31], v[68:71], v[104:107], v[16:31]
	v_mfma_f32_32x32x16_bf16 v[0:15], v[72:75], v[104:107], v[0:15]
	s_waitcnt lgkmcnt(13)
	v_mfma_f32_32x32x16_bf16 v[16:31], v[64:67], v[108:111], v[16:31]
	s_waitcnt lgkmcnt(11)
	v_mfma_f32_32x32x16_bf16 v[0:15], v[76:79], v[108:111], v[0:15]
	v_mfma_f32_32x32x16_bf16 v[16:31], v[60:63], v[112:115], v[16:31]
	s_waitcnt lgkmcnt(10)
	v_mfma_f32_32x32x16_bf16 v[0:15], v[56:59], v[112:115], v[0:15]
	v_readfirstlane_b32 s20, v190
	v_readfirstlane_b32 s21, v191
	v_readfirstlane_b32 s22, v192
	v_readfirstlane_b32 s23, v193
	s_nop 0
	v_subrev_u32_e32 v190, s20, v190
	v_subrev_u32_e32 v192, s22, v192
	s_nop 4
.LBB0_336:
	global_load_dwordx4 v[104:107], v190, s[20:21]
	global_load_dwordx4 v[96:99], v192, s[22:23]
	s_waitcnt lgkmcnt(2)
	v_mfma_f32_32x32x16_bf16 v[64:79], v[160:163], v[80:83], v[32:47]
	s_mov_b32 s8, s33
	v_mfma_f32_32x32x16_bf16 v[64:79], v[156:159], v[84:87], v[64:79]
	v_mfma_f32_32x32x16_bf16 v[64:79], v[144:147], v[92:95], v[64:79]
	v_mfma_f32_32x32x16_bf16 v[64:79], v[140:143], v[88:91], v[64:79]
	v_mfma_f32_32x32x16_bf16 v[48:63], v[164:167], v[80:83], v[32:47]
	s_and_b32 s33, 1, s76
	s_cselect_b32 s9, 0, 0x2400
	v_add_u32_e32 v100, s9, v199
	ds_read_b128 v[128:131], v100 offset:18432
	ds_read_b128 v[116:119], v100 offset:18464
	ds_read_b128 v[132:135], v100 offset:23040
	ds_read_b128 v[120:123], v100 offset:23072
	ds_read_b128 v[112:115], v100 offset:18496
	ds_read_b128 v[108:111], v100 offset:18528
	ds_read_b128 v[124:127], v100 offset:23104
	ds_read_b128 v[100:103], v100 offset:23136
	v_mfma_f32_32x32x16_bf16 v[48:63], v[152:155], v[84:87], v[48:63]
	v_exp_f32_e32 v64, v64
	v_exp_f32_e32 v65, v65
	v_exp_f32_e32 v66, v66
	v_mfma_f32_32x32x16_bf16 v[48:63], v[148:151], v[92:95], v[48:63]
	v_exp_f32_e32 v67, v67
	v_exp_f32_e32 v68, v68
	v_exp_f32_e32 v69, v69
	v_mfma_f32_32x32x16_bf16 v[48:63], v[136:139], v[88:91], v[48:63]
	v_exp_f32_e32 v70, v70
	v_exp_f32_e32 v71, v71
	v_exp_f32_e32 v72, v72
	v_exp_f32_e32 v73, v73
	v_exp_f32_e32 v74, v74
	v_exp_f32_e32 v75, v75
	v_exp_f32_e32 v76, v76
	v_exp_f32_e32 v77, v77
	v_exp_f32_e32 v78, v78
	v_exp_f32_e32 v79, v79
	s_setprio 0
	s_nop 0

.Lstg_y_4:
	s_mul_i32 s9, s77, 0x2400
	v_add_u32_e32 v235, s9, v199
	ds_read_b128 v[160:163], v235
	ds_read_b128 v[156:159], v235 offset:32
	ds_read_b128 v[164:167], v235 offset:4608
	ds_read_b128 v[152:155], v235 offset:4640
	ds_read_b128 v[144:147], v235 offset:64
	ds_read_b128 v[140:143], v235 offset:96
	ds_read_b128 v[148:151], v235 offset:4672
	ds_read_b128 v[136:139], v235 offset:4704
	v_mfma_f32_32x32x16_bf16 v[16:31], v[128:131], v[48:51], v[16:31]
	v_add_f32_e32 v64, v64, v219
	v_add_f32_e32 v65, v65, v220
	v_add_f32_e32 v66, v66, v221
	v_add_f32_e32 v67, v67, v222
	v_add_f32_e32 v68, v68, v223
	s_mul_i32 s9, s8, 0x2400
	s_cmp_eq_u32 s33, 1
	s_cselect_b32 s18, 0, 0x2400
	s_add_i32 s76, s76, 1
	s_add_u32 s20, s20, 0x2000
	s_addc_u32 s21, s21, 0
	s_add_u32 s22, s22, 0x80
	s_addc_u32 s23, s23, 0
	s_cmp_eq_u32 s76, 31
	v_mfma_f32_32x32x16_bf16 v[0:15], v[132:135], v[48:51], v[0:15]
	v_add_f32_e32 v69, v69, v224
	v_add_f32_e32 v70, v70, v225
	v_add_f32_e32 v71, v71, v226
	v_add_f32_e32 v72, v72, v227
	v_add_f32_e32 v73, v73, v228
	v_add_u32_e32 v48, s9, v177
	s_waitcnt vmcnt(1)
	ds_write_b128 v48, v[104:107]
	v_add_u32_e32 v48, s18, v215
	s_waitcnt vmcnt(0)
	ds_write2_b64 v48, v[96:97], v[98:99] offset1:2
	v_mfma_f32_32x32x16_bf16 v[16:31], v[116:119], v[52:55], v[16:31]
	v_add_f32_e32 v74, v74, v229
	v_add_f32_e32 v75, v75, v230
	v_add_f32_e32 v76, v76, v231
	v_add_f32_e32 v77, v77, v232
	v_add_f32_e32 v78, v78, v233
	v_mfma_f32_32x32x16_bf16 v[0:15], v[120:123], v[52:55], v[0:15]
	v_add_f32_e32 v79, v79, v234
	v_add_f32_e32 v64, v64, v65
	v_add_f32_e32 v66, v66, v67
	v_add_f32_e32 v68, v68, v69
	v_add_f32_e32 v70, v70, v71
	v_mfma_f32_32x32x16_bf16 v[16:31], v[112:115], v[56:59], v[16:31]
	v_add_f32_e32 v72, v72, v73
	v_add_f32_e32 v74, v74, v75
	v_add_f32_e32 v76, v76, v77
	v_add_f32_e32 v78, v78, v79
	v_mfma_f32_32x32x16_bf16 v[0:15], v[124:127], v[56:59], v[0:15]
	v_add_f32_e32 v64, v64, v66
	v_add_f32_e32 v68, v68, v70
	v_add_f32_e32 v72, v72, v74
	v_add_f32_e32 v76, v76, v78
	v_mfma_f32_32x32x16_bf16 v[16:31], v[108:111], v[60:63], v[16:31]
	v_add_f32_e32 v64, v64, v68
	v_add_f32_e32 v72, v72, v76
	v_add_f32_e32 v64, v64, v72
	v_add_f32_e32 v194, v194, v64
	v_mfma_f32_32x32x16_bf16 v[0:15], v[100:103], v[60:63], v[0:15]
	s_cbranch_scc1 .LBB0_340
	s_mov_b32 s33, s77
	s_mov_b32 s77, s8
	s_branch .LBB0_336
.LBB0_340:
	s_mov_b64 s[20:21], 0x2000
	s_mov_b64 s[22:23], 0x80
	s_waitcnt lgkmcnt(9)
	v_mfma_f32_32x32x16_bf16 v[64:79], v[160:163], v[80:83], v[32:47]
	s_waitcnt lgkmcnt(7)
	v_mfma_f32_32x32x16_bf16 v[48:63], v[164:167], v[80:83], v[32:47]
	v_mfma_f32_32x32x16_bf16 v[64:79], v[156:159], v[84:87], v[64:79]
	s_waitcnt lgkmcnt(6)
	v_mfma_f32_32x32x16_bf16 v[48:63], v[152:155], v[84:87], v[48:63]
	s_waitcnt lgkmcnt(5)
	v_mfma_f32_32x32x16_bf16 v[64:79], v[144:147], v[92:95], v[64:79]
	s_waitcnt lgkmcnt(3)
	v_mfma_f32_32x32x16_bf16 v[48:63], v[148:151], v[92:95], v[48:63]
	v_mfma_f32_32x32x16_bf16 v[64:79], v[140:143], v[88:91], v[64:79]
	s_waitcnt lgkmcnt(2)
	v_mfma_f32_32x32x16_bf16 v[48:63], v[136:139], v[88:91], v[48:63]
	s_setprio 0
	ds_read_b128 v[124:127], v199 offset:18432
	ds_read_b128 v[112:115], v199 offset:18464
	ds_read_b128 v[128:131], v199 offset:23040
	ds_read_b128 v[116:119], v199 offset:23072
	ds_read_b128 v[108:111], v199 offset:18496
	ds_read_b128 v[100:103], v199 offset:18528
	ds_read_b128 v[120:123], v199 offset:23104
	ds_read_b128 v[104:107], v199 offset:23136
	s_nop 1
	s_nop 0
	s_cmp_eq_u32 s98, 0
	s_cbranch_scc1 .Lstg_x_5
	s_waitcnt lgkmcnt(0)
	s_barrier

.Lstg_y_10:
	ds_read_b128 v[60:63], v208 offset:13312
	ds_read_b128 v[156:159], v208 offset:13344
	ds_read_b128 v[164:167], v208 offset:19968
	ds_read_b128 v[152:155], v208 offset:13376
	ds_read_b128 v[160:163], v208 offset:20000
	ds_read_b128 v[148:151], v208 offset:20032
	s_waitcnt lgkmcnt(13)
	v_mfma_f32_32x32x16_bf16 v[16:31], v[64:67], v[0:3], 0
	s_waitcnt vmcnt(1)
	ds_write_b128 v220, v[48:51] offset:26624
	s_waitcnt lgkmcnt(12)
	v_mfma_f32_32x32x16_bf16 v[0:15], v[72:75], v[0:3], 0
	v_mfma_f32_32x32x16_bf16 v[16:31], v[68:71], v[120:123], v[16:31]
	s_waitcnt lgkmcnt(11)
	v_mfma_f32_32x32x16_bf16 v[0:15], v[76:79], v[120:123], v[0:15]
	s_waitcnt lgkmcnt(10)
	v_mfma_f32_32x32x16_bf16 v[16:31], v[108:111], v[124:127], v[16:31]
	s_waitcnt lgkmcnt(8)
	v_mfma_f32_32x32x16_bf16 v[0:15], v[116:119], v[124:127], v[0:15]
	v_mfma_f32_32x32x16_bf16 v[16:31], v[112:115], v[128:131], v[16:31]
	s_waitcnt lgkmcnt(7)
	v_mfma_f32_32x32x16_bf16 v[0:15], v[56:59], v[128:131], v[0:15]
	s_and_saveexec_b64 s[8:9], s[4:5]
	ds_write_b128 v187, v[104:107] offset:26624
	s_or_b64 exec, exec, s[8:9]
	v_add_u32_e32 v187, 0x9c00, v198
	s_waitcnt vmcnt(0)
	ds_write2_b64 v187, v[52:53], v[54:55] offset1:2
	v_mad_u64_u32 v[194:195], s[8:9], s33, v217, v[182:183]
	s_or_b32 s8, s73, s44
	s_mov_b32 s9, s17
	s_lshl_b32 s3, s72, 6
	v_lshl_add_u64 v[196:197], v[184:185], 0, s[8:9]
	s_mov_b32 s42, 1
	s_mov_b32 s8, 0
	s_mov_b32 s33, 2
	s_mov_b32 s43, 2
	v_readfirstlane_b32 s36, v194
	v_readfirstlane_b32 s37, v195
	v_readfirstlane_b32 s22, v196
	v_readfirstlane_b32 s23, v197
	s_nop 0
	v_subrev_u32_e32 v194, s36, v194
	v_subrev_u32_e32 v196, s22, v196
	v_add_u32_e32 v245, 0x2000, v194
	s_sub_u32 s36, s36, 0x2000
	s_subb_u32 s37, s37, 0
	s_nop 4
.LBB0_361:
	s_mov_b32 s45, s43
	global_load_dwordx4 v[112:115], v194, s[36:37]
	s_mov_b32 s43, s8
	s_and_saveexec_b64 s[8:9], s[4:5]
	s_cbranch_execz .LBB0_363
	global_load_dwordx4 v[104:107], v245, s[36:37]
.LBB0_363:
	s_or_b64 exec, exec, s[8:9]
	s_waitcnt lgkmcnt(7)
	v_mfma_f32_32x32x16_bf16 v[64:79], v[60:63], v[80:83], v[32:47]
	s_mul_i32 s8, s42, 0x3400
	v_add_u32_e32 v124, s8, v208
	ds_read_b128 v[108:111], v124 offset:96
	ds_read_b128 v[116:119], v124 offset:128
	ds_read_b128 v[120:123], v124 offset:160
	s_waitcnt lgkmcnt(7)
	v_mfma_f32_32x32x16_bf16 v[64:79], v[156:159], v[84:87], v[64:79]
	v_mfma_f32_32x32x16_bf16 v[64:79], v[152:155], v[88:91], v[64:79]
	s_waitcnt lgkmcnt(2)
	v_mfma_f32_32x32x16_bf16 v[64:79], v[108:111], v[92:95], v[64:79]
	s_waitcnt lgkmcnt(1)
	v_mfma_f32_32x32x16_bf16 v[64:79], v[116:119], v[96:99], v[64:79]
	s_waitcnt lgkmcnt(0)
	v_mfma_f32_32x32x16_bf16 v[64:79], v[120:123], v[100:103], v[64:79]
	ds_read_b128 v[108:111], v124 offset:6752
	ds_read_b128 v[116:119], v124 offset:6784
	ds_read_b128 v[120:123], v124 offset:6816
	v_mfma_f32_32x32x16_bf16 v[48:63], v[164:167], v[80:83], v[32:47]
	v_mfma_f32_32x32x16_bf16 v[48:63], v[160:163], v[84:87], v[48:63]
	v_mfma_f32_32x32x16_bf16 v[48:63], v[148:151], v[88:91], v[48:63]
	s_waitcnt lgkmcnt(2)
	v_mfma_f32_32x32x16_bf16 v[48:63], v[108:111], v[92:95], v[48:63]
	global_load_dwordx4 v[108:111], v196, s[22:23]
	s_nop 2
	v_exp_f32_e32 v64, v64
	v_exp_f32_e32 v65, v65
	v_exp_f32_e32 v66, v66
	v_exp_f32_e32 v67, v67
	v_exp_f32_e32 v68, v68
	s_waitcnt lgkmcnt(1)
	v_mfma_f32_32x32x16_bf16 v[48:63], v[116:119], v[96:99], v[48:63]
	v_exp_f32_e32 v69, v69
	v_exp_f32_e32 v70, v70
	v_exp_f32_e32 v71, v71
	v_exp_f32_e32 v72, v72
	v_exp_f32_e32 v73, v73
	s_waitcnt lgkmcnt(0)
	v_mfma_f32_32x32x16_bf16 v[48:63], v[120:123], v[100:103], v[48:63]
	v_exp_f32_e32 v74, v74
	v_exp_f32_e32 v75, v75
	v_exp_f32_e32 v76, v76
	v_exp_f32_e32 v77, v77
	v_exp_f32_e32 v78, v78
	v_exp_f32_e32 v79, v79
	s_setprio 0
	s_and_b32 s72, 1, s33
	s_cselect_b32 s8, 0, 0x2400
	v_add_u32_e32 v116, s8, v209
	ds_read_b128 v[140:143], v116 offset:39936
	ds_read_b128 v[128:131], v116 offset:39968
	ds_read_b128 v[144:147], v116 offset:44544
	ds_read_b128 v[132:135], v116 offset:44576
	ds_read_b128 v[124:127], v116 offset:40000
	ds_read_b128 v[120:123], v116 offset:40032
	ds_read_b128 v[136:139], v116 offset:44608
	ds_read_b128 v[116:119], v116 offset:44640

.Lstg_y_12:
	s_mul_i32 s8, s45, 0x3400
	v_add_u32_e32 v189, s8, v208
	ds_read_b128 v[60:63], v189
	ds_read_b128 v[156:159], v189 offset:32
	ds_read_b128 v[164:167], v189 offset:6656
	ds_read_b128 v[152:155], v189 offset:64
	ds_read_b128 v[160:163], v189 offset:6688
	ds_read_b128 v[148:151], v189 offset:6720
	v_mfma_f32_32x32x16_bf16 v[16:31], v[140:143], v[224:227], v[16:31]
	v_add_f32_e32 v64, v64, v48
	v_add_f32_e32 v65, v65, v49
	v_add_f32_e32 v66, v66, v50
	v_add_f32_e32 v67, v67, v51
	s_mul_i32 s44, s43, 0x3400
	s_add_i32 s18, s44, 0
	v_mfma_f32_32x32x16_bf16 v[0:15], v[144:147], v[224:227], v[0:15]
	v_add_f32_e32 v68, v68, v52
	v_add_f32_e32 v69, v69, v53
	v_add_f32_e32 v70, v70, v54
	v_add_f32_e32 v71, v71, v55
	v_mfma_f32_32x32x16_bf16 v[16:31], v[128:131], v[228:231], v[16:31]
	v_add_f32_e32 v72, v72, v56
	v_add_f32_e32 v73, v73, v57
	v_add_f32_e32 v74, v74, v58
	v_add_f32_e32 v75, v75, v59
	v_mfma_f32_32x32x16_bf16 v[0:15], v[132:135], v[228:231], v[0:15]
	v_add_f32_e32 v76, v76, v219
	v_add_f32_e32 v77, v77, v220
	v_add_f32_e32 v78, v78, v221
	v_add_f32_e32 v79, v79, v222
	v_mfma_f32_32x32x16_bf16 v[16:31], v[124:127], v[232:235], v[16:31]
	v_add_f32_e32 v64, v64, v65
	v_add_f32_e32 v66, v66, v67
	v_add_f32_e32 v68, v68, v69
	v_add_f32_e32 v70, v70, v71
	v_mfma_f32_32x32x16_bf16 v[0:15], v[136:139], v[232:235], v[0:15]
	v_add_f32_e32 v72, v72, v73
	v_add_f32_e32 v74, v74, v75
	v_add_f32_e32 v76, v76, v77
	v_add_f32_e32 v78, v78, v79
	v_mfma_f32_32x32x16_bf16 v[16:31], v[120:123], v[236:239], v[16:31]
	v_add_f32_e32 v64, v64, v66
	v_add_f32_e32 v68, v68, v70
	v_add_f32_e32 v72, v72, v74
	v_add_f32_e32 v76, v76, v78
	v_add_u32_e32 v120, s18, v207
	s_waitcnt vmcnt(1)
	ds_write_b128 v120, v[112:115]
	v_mfma_f32_32x32x16_bf16 v[0:15], v[116:119], v[236:239], v[0:15]
	v_add_f32_e32 v64, v64, v68
	v_add_f32_e32 v72, v72, v76
	s_and_saveexec_b64 s[8:9], s[4:5]
	v_add_u32_e32 v112, s18, v206
	ds_write_b128 v112, v[104:107]
	s_or_b64 exec, exec, s[8:9]
	v_add_f32_e32 v64, v64, v72
	s_cmp_eq_u32 s72, 1
	s_cselect_b32 s8, 0, 0x2400
	v_add_f32_e32 v190, v190, v64
	v_add_u32_e32 v48, s8, v244
	s_waitcnt vmcnt(0)
	ds_write2_b64 v48, v[108:109], v[110:111] offset0:128 offset1:130
	s_add_i32 s33, s33, 1
	s_add_u32 s36, s36, 0x3000
	s_addc_u32 s37, s37, 0
	s_add_u32 s22, s22, 0x80
	s_addc_u32 s23, s23, 0
	s_cmp_eq_u32 s33, 31
	s_cbranch_scc1 .LBB0_369
	s_mov_b32 s8, s42
	s_mov_b32 s42, s45
	s_branch .LBB0_361
.LBB0_369:
	s_mov_b64 s[36:37], 0x3000
	s_mov_b64 s[22:23], 0x80
	s_waitcnt lgkmcnt(7)
	v_mfma_f32_32x32x16_bf16 v[64:79], v[60:63], v[80:83], v[32:47]
	ds_read_b128 v[104:107], v189 offset:96
	ds_read_b128 v[108:111], v189 offset:128
	s_waitcnt lgkmcnt(7)
	v_mfma_f32_32x32x16_bf16 v[48:63], v[164:167], v[80:83], v[32:47]
	v_mfma_f32_32x32x16_bf16 v[64:79], v[156:159], v[84:87], v[64:79]
	s_waitcnt lgkmcnt(5)
	v_mfma_f32_32x32x16_bf16 v[48:63], v[160:163], v[84:87], v[48:63]
	v_mfma_f32_32x32x16_bf16 v[64:79], v[152:155], v[88:91], v[64:79]
	s_waitcnt lgkmcnt(4)
	v_mfma_f32_32x32x16_bf16 v[48:63], v[148:151], v[88:91], v[48:63]
	s_waitcnt lgkmcnt(1)
	v_mfma_f32_32x32x16_bf16 v[64:79], v[104:107], v[92:95], v[64:79]
	ds_read_b128 v[104:107], v189 offset:6752
	ds_read_b128 v[112:115], v189 offset:160
	s_waitcnt lgkmcnt(1)
	v_mfma_f32_32x32x16_bf16 v[48:63], v[104:107], v[92:95], v[48:63]
	v_mfma_f32_32x32x16_bf16 v[64:79], v[108:111], v[96:99], v[64:79]
	ds_read_b128 v[104:107], v189 offset:6784
	ds_read_b128 v[108:111], v189 offset:6816
	s_waitcnt lgkmcnt(1)
	v_mfma_f32_32x32x16_bf16 v[48:63], v[104:107], v[96:99], v[48:63]
	v_mfma_f32_32x32x16_bf16 v[64:79], v[112:115], v[100:103], v[64:79]
	s_waitcnt lgkmcnt(0)
	v_mfma_f32_32x32x16_bf16 v[48:63], v[108:111], v[100:103], v[48:63]
	s_setprio 0
	ds_read_b128 v[132:135], v209 offset:39936
	ds_read_b128 v[120:123], v209 offset:39968
	ds_read_b128 v[136:139], v209 offset:44544
	ds_read_b128 v[124:127], v209 offset:44576
	ds_read_b128 v[116:119], v209 offset:40000
	ds_read_b128 v[108:111], v209 offset:40032
	ds_read_b128 v[128:131], v209 offset:44608
	ds_read_b128 v[112:115], v209 offset:44640
	s_nop 1
	s_nop 0
	s_cmp_eq_u32 s98, 0
	s_cbranch_scc1 .Lstg_x_13
	s_waitcnt lgkmcnt(0)
	s_barrier
